# P3 mid: all 16 gate loads of a batch issued before the first wait (was: 4 loads, full wait, then 12 more); flat loads -> global loads
# speedup vs baseline: 1.0013x; 1.0013x over previous
;     __device__ __forceinline__ void mid(f32x4 (&acc)[2][2][4][2], const Unit& u, int wr, int wc, int fr, int fq) const {
;         const bf16* gb = G + (size_t)(u.pm * 256 + wr * 64 + fr) * 2048 + u.pn * 256 + wc * 32 + 8 * fq;
; #pragma unroll
;         for (int ai = 0; ai < 2; ++ai) { asm volatile("" : "+v"(gb));
;             u32x4 gp[4][2], gf[4][2];
; #pragma unroll
;             for (int m = 0; m < 4; ++m)
; #pragma unroll
;                 for (int bj = 0; bj < 2; ++bj) { const bf16* gr = gb + (size_t)(ai * 128 + m * 16) * 2048 + bj * 128; gp[m][bj] = *(const u32x4*)gr; gf[m][bj] = *(const u32x4*)(gr + 1024); }
; #pragma unroll
;             for (int m = 0; m < 4; ++m)
; #pragma unroll
;                 for (int bj = 0; bj < 2; ++bj) { const u32x4 p = gp[m][bj], f = gf[m][bj];
;                     acc[ai][bj][m][0][0] *= bflo(p.x) * __builtin_amdgcn_rcpf(bflo(f.x)); acc[ai][bj][m][0][1] *= bfhi(p.x) * __builtin_amdgcn_rcpf(bfhi(f.x));
;                     acc[ai][bj][m][0][2] *= bflo(p.y) * __builtin_amdgcn_rcpf(bflo(f.y)); acc[ai][bj][m][0][3] *= bfhi(p.y) * __builtin_amdgcn_rcpf(bfhi(f.y));
;                     acc[ai][bj][m][1][0] *= bflo(p.z) * __builtin_amdgcn_rcpf(bflo(f.z)); acc[ai][bj][m][1][1] *= bfhi(p.z) * __builtin_amdgcn_rcpf(bfhi(f.z));
;                     acc[ai][bj][m][1][2] *= bflo(p.w) * __builtin_amdgcn_rcpf(bflo(f.w)); acc[ai][bj][m][1][3] *= bfhi(p.w) * __builtin_amdgcn_rcpf(bfhi(f.w)); }
;             __builtin_amdgcn_sched_barrier(0); }
;     }
.LBB0_513:
	s_cmpk_lg_i32 s46, 0x400
	s_cbranch_scc1 .LBB0_512
	v_mov_b64_e32 v[196:197], v[190:191]
	global_load_dwordx4 v[202:205], v[196:197], off offset:2048
	global_load_dwordx4 v[206:209], v[196:197], off
	global_load_dwordx4 v[214:217], v[196:197], off offset:2304
	global_load_dwordx4 v[222:225], v[196:197], off offset:256
	v_add_co_u32_e32 v128, vcc, 0x10000, v196
	s_nop 1
	v_addc_co_u32_e32 v129, vcc, 0, v197, vcc
	global_load_dwordx4 v[226:229], v[128:129], off
	global_load_dwordx4 v[160:163], v[128:129], off offset:256
	global_load_dwordx4 v[230:233], v[128:129], off offset:2048
	global_load_dwordx4 v[164:167], v[128:129], off offset:2304
	v_add_co_u32_e32 v130, vcc, s81, v196
	s_nop 1
	v_addc_co_u32_e32 v131, vcc, 0, v197, vcc
	global_load_dwordx4 v[152:155], v[130:131], off
	global_load_dwordx4 v[144:147], v[130:131], off offset:256
	global_load_dwordx4 v[156:159], v[130:131], off offset:2048
	global_load_dwordx4 v[148:151], v[130:131], off offset:2304
	v_add_co_u32_e32 v132, vcc, s82, v196
	s_nop 1
	v_addc_co_u32_e32 v133, vcc, 0, v197, vcc
	global_load_dwordx4 v[136:139], v[132:133], off
	global_load_dwordx4 v[128:131], v[132:133], off offset:256
	global_load_dwordx4 v[140:143], v[132:133], off offset:2048
	s_nop 0
	global_load_dwordx4 v[132:135], v[132:133], off offset:2304
	s_waitcnt vmcnt(12)
	v_lshlrev_b32_e32 v236, 16, v203
	v_and_b32_e32 v237, 0xffff0000, v203
	v_rcp_f32_e32 v236, v236
	v_rcp_f32_e32 v237, v237
	v_lshlrev_b32_e32 v221, 16, v202
	v_and_b32_e32 v235, 0xffff0000, v202
	v_lshlrev_b32_e32 v202, 16, v207
	v_and_b32_e32 v203, 0xffff0000, v207
	v_lshlrev_b32_e32 v240, 16, v205
	v_and_b32_e32 v241, 0xffff0000, v205
	v_rcp_f32_e32 v240, v240
	v_rcp_f32_e32 v241, v241
	v_pk_mul_f32 v[202:203], v[236:237], v[202:203]
	v_lshlrev_b32_e32 v210, 16, v206
	v_and_b32_e32 v211, 0xffff0000, v206
	v_lshlrev_b32_e32 v238, 16, v204
	v_and_b32_e32 v239, 0xffff0000, v204
	v_lshlrev_b32_e32 v206, 16, v208
	v_and_b32_e32 v207, 0xffff0000, v208
	v_lshlrev_b32_e32 v204, 16, v209
	v_and_b32_e32 v205, 0xffff0000, v209
	v_lshlrev_b32_e32 v242, 16, v214
	v_and_b32_e32 v243, 0xffff0000, v214
	v_lshlrev_b32_e32 v208, 16, v222
	v_and_b32_e32 v209, 0xffff0000, v222
	v_lshlrev_b32_e32 v244, 16, v215
	v_and_b32_e32 v245, 0xffff0000, v215
	v_lshlrev_b32_e32 v214, 16, v223
	v_and_b32_e32 v215, 0xffff0000, v223
	v_lshlrev_b32_e32 v222, 16, v224
	v_and_b32_e32 v223, 0xffff0000, v224
	v_lshlrev_b32_e32 v224, 16, v217
	v_pk_mul_f32 v[126:127], v[126:127], v[202:203]
	v_and_b32_e32 v203, 0xffff0000, v217
	v_rcp_f32_e32 v202, v224
	v_rcp_f32_e32 v203, v203
	v_pk_mul_f32 v[204:205], v[240:241], v[204:205]
	v_lshlrev_b32_e32 v246, 16, v216
	v_pk_mul_f32 v[122:123], v[122:123], v[204:205]
	v_lshlrev_b32_e32 v204, 16, v225
	v_and_b32_e32 v205, 0xffff0000, v225
	v_pk_mul_f32 v[202:203], v[202:203], v[204:205]
	v_and_b32_e32 v216, 0xffff0000, v216
	v_pk_mul_f32 v[110:111], v[110:111], v[202:203]
	v_rcp_f32_e32 v234, v221
	v_rcp_f32_e32 v235, v235
	v_rcp_f32_e32 v238, v238
	v_rcp_f32_e32 v239, v239
	v_rcp_f32_e32 v242, v242
	v_rcp_f32_e32 v243, v243
	v_rcp_f32_e32 v244, v244
	v_rcp_f32_e32 v245, v245
	v_rcp_f32_e32 v246, v246
	v_rcp_f32_e32 v247, v216
	v_pk_mul_f32 v[210:211], v[234:235], v[210:211]
	v_pk_mul_f32 v[206:207], v[238:239], v[206:207]
	v_pk_mul_f32 v[208:209], v[242:243], v[208:209]
	v_pk_mul_f32 v[214:215], v[244:245], v[214:215]
	v_pk_mul_f32 v[222:223], v[246:247], v[222:223]
	v_pk_mul_f32 v[124:125], v[124:125], v[210:211]
	v_pk_mul_f32 v[120:121], v[120:121], v[206:207]
	v_pk_mul_f32 v[116:117], v[116:117], v[208:209]
	v_pk_mul_f32 v[118:119], v[118:119], v[214:215]
	v_pk_mul_f32 v[108:109], v[108:109], v[222:223]
	s_waitcnt vmcnt(0) lgkmcnt(0)
	v_lshlrev_b32_e32 v202, 16, v226
	v_and_b32_e32 v203, 0xffff0000, v226
	v_lshlrev_b32_e32 v204, 16, v230
	v_and_b32_e32 v205, 0xffff0000, v230
	v_rcp_f32_e32 v204, v204
	v_rcp_f32_e32 v205, v205
	s_nop 0
	v_pk_mul_f32 v[202:203], v[204:205], v[202:203]
	v_lshlrev_b32_e32 v204, 16, v231
	v_and_b32_e32 v205, 0xffff0000, v231
	v_rcp_f32_e32 v204, v204
	v_rcp_f32_e32 v205, v205
	v_pk_mul_f32 v[112:113], v[112:113], v[202:203]
	v_lshlrev_b32_e32 v202, 16, v227
	v_and_b32_e32 v203, 0xffff0000, v227
	v_pk_mul_f32 v[202:203], v[204:205], v[202:203]
	v_lshlrev_b32_e32 v204, 16, v232
	v_and_b32_e32 v205, 0xffff0000, v232
	v_rcp_f32_e32 v204, v204
	v_rcp_f32_e32 v205, v205
	v_pk_mul_f32 v[114:115], v[114:115], v[202:203]
	v_lshlrev_b32_e32 v202, 16, v228
	v_and_b32_e32 v203, 0xffff0000, v228
	v_pk_mul_f32 v[202:203], v[204:205], v[202:203]
	v_lshlrev_b32_e32 v204, 16, v233
	v_and_b32_e32 v205, 0xffff0000, v233
	v_rcp_f32_e32 v204, v204
	v_rcp_f32_e32 v205, v205
	v_pk_mul_f32 v[104:105], v[104:105], v[202:203]
	v_lshlrev_b32_e32 v202, 16, v229
	v_and_b32_e32 v203, 0xffff0000, v229
	v_pk_mul_f32 v[202:203], v[204:205], v[202:203]
	v_lshlrev_b32_e32 v204, 16, v164
	v_and_b32_e32 v164, 0xffff0000, v164
	v_pk_mul_f32 v[106:107], v[106:107], v[202:203]
	v_lshlrev_b32_e32 v202, 16, v160
	v_and_b32_e32 v203, 0xffff0000, v160
	v_lshlrev_b32_e32 v160, 16, v165
	v_rcp_f32_e32 v205, v164
	v_rcp_f32_e32 v164, v160
	v_and_b32_e32 v160, 0xffff0000, v165
	v_rcp_f32_e32 v165, v160
	v_lshlrev_b32_e32 v160, 16, v161
	v_and_b32_e32 v161, 0xffff0000, v161
	v_rcp_f32_e32 v204, v204
	v_pk_mul_f32 v[160:161], v[164:165], v[160:161]
	v_lshlrev_b32_e32 v164, 16, v166
	v_and_b32_e32 v165, 0xffff0000, v166
	v_rcp_f32_e32 v164, v164
	v_rcp_f32_e32 v165, v165
	v_pk_mul_f32 v[102:103], v[102:103], v[160:161]
	v_lshlrev_b32_e32 v160, 16, v162
	v_and_b32_e32 v161, 0xffff0000, v162
	v_lshlrev_b32_e32 v162, 16, v167
;     __device__ __forceinline__ void mid(f32x4 (&acc)[2][2][4][2], const Unit& u, int wr, int wc, int fr, int fq) const {
;         const bf16* gb = G + (size_t)(u.pm * 256 + wr * 64 + fr) * 2048 + u.pn * 256 + wc * 32 + 8 * fq;
; #pragma unroll
;         for (int ai = 0; ai < 2; ++ai) { asm volatile("" : "+v"(gb));
;             u32x4 gp[4][2], gf[4][2];
; #pragma unroll
;             for (int m = 0; m < 4; ++m)
; #pragma unroll
;                 for (int bj = 0; bj < 2; ++bj) { const bf16* gr = gb + (size_t)(ai * 128 + m * 16) * 2048 + bj * 128; gp[m][bj] = *(const u32x4*)gr; gf[m][bj] = *(const u32x4*)(gr + 1024); }
; #pragma unroll
;             for (int m = 0; m < 4; ++m)
; #pragma unroll
;                 for (int bj = 0; bj < 2; ++bj) { const u32x4 p = gp[m][bj], f = gf[m][bj];
;                     acc[ai][bj][m][0][0] *= bflo(p.x) * __builtin_amdgcn_rcpf(bflo(f.x)); acc[ai][bj][m][0][1] *= bfhi(p.x) * __builtin_amdgcn_rcpf(bfhi(f.x));
;                     acc[ai][bj][m][0][2] *= bflo(p.y) * __builtin_amdgcn_rcpf(bflo(f.y)); acc[ai][bj][m][0][3] *= bfhi(p.y) * __builtin_amdgcn_rcpf(bfhi(f.y));
;                     acc[ai][bj][m][1][0] *= bflo(p.z) * __builtin_amdgcn_rcpf(bflo(f.z)); acc[ai][bj][m][1][1] *= bfhi(p.z) * __builtin_amdgcn_rcpf(bfhi(f.z));
;                     acc[ai][bj][m][1][2] *= bflo(p.w) * __builtin_amdgcn_rcpf(bflo(f.w)); acc[ai][bj][m][1][3] *= bfhi(p.w) * __builtin_amdgcn_rcpf(bfhi(f.w)); }
;             __builtin_amdgcn_sched_barrier(0); }
;     }
	v_pk_mul_f32 v[160:161], v[164:165], v[160:161]
	v_rcp_f32_e32 v164, v162
	v_and_b32_e32 v162, 0xffff0000, v167
	v_rcp_f32_e32 v165, v162
	v_pk_mul_f32 v[92:93], v[92:93], v[160:161]
	v_lshlrev_b32_e32 v160, 16, v163
	v_and_b32_e32 v161, 0xffff0000, v163
	v_pk_mul_f32 v[160:161], v[164:165], v[160:161]
	v_lshlrev_b32_e32 v162, 16, v156
	v_and_b32_e32 v156, 0xffff0000, v156
	v_pk_mul_f32 v[94:95], v[94:95], v[160:161]
	v_lshlrev_b32_e32 v160, 16, v152
	v_and_b32_e32 v161, 0xffff0000, v152
	v_lshlrev_b32_e32 v152, 16, v157
	v_rcp_f32_e32 v163, v156
	v_rcp_f32_e32 v156, v152
	v_and_b32_e32 v152, 0xffff0000, v157
	v_rcp_f32_e32 v157, v152
	v_lshlrev_b32_e32 v152, 16, v153
	v_and_b32_e32 v153, 0xffff0000, v153
	v_rcp_f32_e32 v162, v162
	v_pk_mul_f32 v[152:153], v[156:157], v[152:153]
	v_lshlrev_b32_e32 v156, 16, v158
	v_and_b32_e32 v157, 0xffff0000, v158
	v_rcp_f32_e32 v156, v156
	v_rcp_f32_e32 v157, v157
	v_pk_mul_f32 v[98:99], v[98:99], v[152:153]
	v_lshlrev_b32_e32 v152, 16, v154
	v_and_b32_e32 v153, 0xffff0000, v154
	v_lshlrev_b32_e32 v154, 16, v159
	v_pk_mul_f32 v[152:153], v[156:157], v[152:153]
	v_rcp_f32_e32 v156, v154
	v_and_b32_e32 v154, 0xffff0000, v159
	v_rcp_f32_e32 v157, v154
	v_pk_mul_f32 v[88:89], v[88:89], v[152:153]
	v_lshlrev_b32_e32 v152, 16, v155
	v_and_b32_e32 v153, 0xffff0000, v155
	v_pk_mul_f32 v[152:153], v[156:157], v[152:153]
	v_lshlrev_b32_e32 v154, 16, v148
	v_and_b32_e32 v148, 0xffff0000, v148
	v_pk_mul_f32 v[90:91], v[90:91], v[152:153]
	v_lshlrev_b32_e32 v152, 16, v144
	v_and_b32_e32 v153, 0xffff0000, v144
	v_lshlrev_b32_e32 v144, 16, v149
	v_rcp_f32_e32 v155, v148
	v_rcp_f32_e32 v148, v144
	v_and_b32_e32 v144, 0xffff0000, v149
	v_rcp_f32_e32 v149, v144
	v_lshlrev_b32_e32 v144, 16, v145
	v_and_b32_e32 v145, 0xffff0000, v145
	v_rcp_f32_e32 v154, v154
	v_pk_mul_f32 v[144:145], v[148:149], v[144:145]
	v_lshlrev_b32_e32 v148, 16, v150
	v_and_b32_e32 v149, 0xffff0000, v150
	v_rcp_f32_e32 v148, v148
	v_rcp_f32_e32 v149, v149
	v_pk_mul_f32 v[86:87], v[86:87], v[144:145]
	v_lshlrev_b32_e32 v144, 16, v146
	v_and_b32_e32 v145, 0xffff0000, v146
	v_lshlrev_b32_e32 v146, 16, v151
	v_pk_mul_f32 v[144:145], v[148:149], v[144:145]
	v_rcp_f32_e32 v148, v146
	v_and_b32_e32 v146, 0xffff0000, v151
	v_rcp_f32_e32 v149, v146
	v_pk_mul_f32 v[76:77], v[76:77], v[144:145]
	v_lshlrev_b32_e32 v144, 16, v147
	v_and_b32_e32 v145, 0xffff0000, v147
	v_pk_mul_f32 v[144:145], v[148:149], v[144:145]
	v_lshlrev_b32_e32 v146, 16, v140
	v_and_b32_e32 v140, 0xffff0000, v140
	v_pk_mul_f32 v[78:79], v[78:79], v[144:145]
	v_lshlrev_b32_e32 v144, 16, v136
	v_and_b32_e32 v145, 0xffff0000, v136
	v_lshlrev_b32_e32 v136, 16, v141
	v_rcp_f32_e32 v147, v140
	v_rcp_f32_e32 v140, v136
	v_and_b32_e32 v136, 0xffff0000, v141
	v_rcp_f32_e32 v141, v136
	v_lshlrev_b32_e32 v136, 16, v137
	v_and_b32_e32 v137, 0xffff0000, v137
	v_rcp_f32_e32 v146, v146
	v_pk_mul_f32 v[136:137], v[140:141], v[136:137]
	v_lshlrev_b32_e32 v140, 16, v142
	v_and_b32_e32 v141, 0xffff0000, v142
	v_rcp_f32_e32 v140, v140
	v_rcp_f32_e32 v141, v141
	v_pk_mul_f32 v[82:83], v[82:83], v[136:137]
	v_lshlrev_b32_e32 v136, 16, v138
	v_and_b32_e32 v137, 0xffff0000, v138
	v_lshlrev_b32_e32 v138, 16, v143
	v_pk_mul_f32 v[136:137], v[140:141], v[136:137]
	v_rcp_f32_e32 v140, v138
	v_and_b32_e32 v138, 0xffff0000, v143
	v_rcp_f32_e32 v141, v138
	v_pk_mul_f32 v[72:73], v[72:73], v[136:137]
	v_lshlrev_b32_e32 v136, 16, v139
	v_and_b32_e32 v137, 0xffff0000, v139
	v_pk_mul_f32 v[136:137], v[140:141], v[136:137]
	v_lshlrev_b32_e32 v138, 16, v132
	v_and_b32_e32 v132, 0xffff0000, v132
	v_pk_mul_f32 v[74:75], v[74:75], v[136:137]
	v_lshlrev_b32_e32 v136, 16, v128
	v_and_b32_e32 v137, 0xffff0000, v128
	v_lshlrev_b32_e32 v128, 16, v133
	v_rcp_f32_e32 v139, v132
	v_rcp_f32_e32 v132, v128
	v_and_b32_e32 v128, 0xffff0000, v133
	v_rcp_f32_e32 v133, v128
	v_lshlrev_b32_e32 v128, 16, v129
	v_and_b32_e32 v129, 0xffff0000, v129
	v_rcp_f32_e32 v138, v138
	v_pk_mul_f32 v[128:129], v[132:133], v[128:129]
	v_lshlrev_b32_e32 v132, 16, v134
	v_and_b32_e32 v133, 0xffff0000, v134
	v_rcp_f32_e32 v132, v132
	v_rcp_f32_e32 v133, v133
	v_pk_mul_f32 v[70:71], v[70:71], v[128:129]
	v_lshlrev_b32_e32 v128, 16, v130
	v_and_b32_e32 v129, 0xffff0000, v130
	v_lshlrev_b32_e32 v130, 16, v135
	v_pk_mul_f32 v[128:129], v[132:133], v[128:129]
	v_rcp_f32_e32 v132, v130
	v_and_b32_e32 v130, 0xffff0000, v135
	v_rcp_f32_e32 v133, v130
	v_pk_mul_f32 v[64:65], v[64:65], v[128:129]
	v_lshlrev_b32_e32 v128, 16, v131
	v_and_b32_e32 v129, 0xffff0000, v131
	v_pk_mul_f32 v[202:203], v[204:205], v[202:203]
	v_pk_mul_f32 v[160:161], v[162:163], v[160:161]
	v_pk_mul_f32 v[152:153], v[154:155], v[152:153]
	v_pk_mul_f32 v[144:145], v[146:147], v[144:145]
	v_pk_mul_f32 v[136:137], v[138:139], v[136:137]
	v_pk_mul_f32 v[128:129], v[132:133], v[128:129]
	v_pk_mul_f32 v[100:101], v[100:101], v[202:203]
	v_pk_mul_f32 v[96:97], v[96:97], v[160:161]
	v_pk_mul_f32 v[84:85], v[84:85], v[152:153]
	v_pk_mul_f32 v[80:81], v[80:81], v[144:145]
	v_pk_mul_f32 v[68:69], v[68:69], v[136:137]
	v_pk_mul_f32 v[66:67], v[66:67], v[128:129]
	s_nop 0
	v_add_co_u32_e32 v128, vcc, s83, v196
	s_nop 1
	v_addc_co_u32_e32 v129, vcc, 0, v197, vcc
	global_load_dwordx4 v[160:163], v[128:129], off offset:2048
	global_load_dwordx4 v[164:167], v[128:129], off
	global_load_dwordx4 v[202:205], v[128:129], off offset:2304
	global_load_dwordx4 v[206:209], v[128:129], off offset:256
	v_add_co_u32_e32 v128, vcc, s84, v196
	s_nop 1
	v_addc_co_u32_e32 v129, vcc, 0, v197, vcc
	global_load_dwordx4 v[214:217], v[128:129], off offset:2048
	global_load_dwordx4 v[222:225], v[128:129], off
	v_add_co_u32_e32 v130, vcc, s85, v196
	s_nop 1
	v_addc_co_u32_e32 v131, vcc, 0, v197, vcc
	v_add_co_u32_e32 v132, vcc, s86, v196
	s_nop 1
	v_addc_co_u32_e32 v133, vcc, 0, v197, vcc
	global_load_dwordx4 v[226:229], v[128:129], off offset:256
	global_load_dwordx4 v[230:233], v[128:129], off offset:2304
	global_load_dwordx4 v[152:155], v[130:131], off
	global_load_dwordx4 v[144:147], v[130:131], off offset:256
	global_load_dwordx4 v[156:159], v[130:131], off offset:2048
	global_load_dwordx4 v[148:151], v[130:131], off offset:2304
	global_load_dwordx4 v[136:139], v[132:133], off
	s_nop 0
	global_load_dwordx4 v[128:131], v[132:133], off offset:256
	global_load_dwordx4 v[140:143], v[132:133], off offset:2048
	s_nop 0
	global_load_dwordx4 v[132:135], v[132:133], off offset:2304
	s_waitcnt vmcnt(12)
;     __device__ __forceinline__ void mid(f32x4 (&acc)[2][2][4][2], const Unit& u, int wr, int wc, int fr, int fq) const {
;         const bf16* gb = G + (size_t)(u.pm * 256 + wr * 64 + fr) * 2048 + u.pn * 256 + wc * 32 + 8 * fq;
; #pragma unroll
;         for (int ai = 0; ai < 2; ++ai) { asm volatile("" : "+v"(gb));
;             u32x4 gp[4][2], gf[4][2];
; #pragma unroll
;             for (int m = 0; m < 4; ++m)
; #pragma unroll
;                 for (int bj = 0; bj < 2; ++bj) { const bf16* gr = gb + (size_t)(ai * 128 + m * 16) * 2048 + bj * 128; gp[m][bj] = *(const u32x4*)gr; gf[m][bj] = *(const u32x4*)(gr + 1024); }
; #pragma unroll
;             for (int m = 0; m < 4; ++m)
; #pragma unroll
;                 for (int bj = 0; bj < 2; ++bj) { const u32x4 p = gp[m][bj], f = gf[m][bj];
;                     acc[ai][bj][m][0][0] *= bflo(p.x) * __builtin_amdgcn_rcpf(bflo(f.x)); acc[ai][bj][m][0][1] *= bfhi(p.x) * __builtin_amdgcn_rcpf(bfhi(f.x));
;                     acc[ai][bj][m][0][2] *= bflo(p.y) * __builtin_amdgcn_rcpf(bflo(f.y)); acc[ai][bj][m][0][3] *= bfhi(p.y) * __builtin_amdgcn_rcpf(bfhi(f.y));
;                     acc[ai][bj][m][1][0] *= bflo(p.z) * __builtin_amdgcn_rcpf(bflo(f.z)); acc[ai][bj][m][1][1] *= bfhi(p.z) * __builtin_amdgcn_rcpf(bfhi(f.z));
;                     acc[ai][bj][m][1][2] *= bflo(p.w) * __builtin_amdgcn_rcpf(bflo(f.w)); acc[ai][bj][m][1][3] *= bfhi(p.w) * __builtin_amdgcn_rcpf(bfhi(f.w)); }
;             __builtin_amdgcn_sched_barrier(0); }
;     }
	v_lshlrev_b32_e32 v221, 16, v161
	v_and_b32_e32 v235, 0xffff0000, v161
	v_rcp_f32_e32 v234, v221
	v_rcp_f32_e32 v235, v235
	v_lshlrev_b32_e32 v210, 16, v160
	v_and_b32_e32 v211, 0xffff0000, v160
	v_lshlrev_b32_e32 v160, 16, v165
	v_and_b32_e32 v161, 0xffff0000, v165
	v_lshlrev_b32_e32 v238, 16, v163
	v_and_b32_e32 v239, 0xffff0000, v163
	v_rcp_f32_e32 v238, v238
	v_rcp_f32_e32 v239, v239
	v_pk_mul_f32 v[160:161], v[234:235], v[160:161]
	v_lshlrev_b32_e32 v196, 16, v164
	v_and_b32_e32 v197, 0xffff0000, v164
	v_lshlrev_b32_e32 v236, 16, v162
	v_and_b32_e32 v237, 0xffff0000, v162
	v_lshlrev_b32_e32 v164, 16, v166
	v_and_b32_e32 v165, 0xffff0000, v166
	v_lshlrev_b32_e32 v162, 16, v167
	v_and_b32_e32 v163, 0xffff0000, v167
	v_lshlrev_b32_e32 v240, 16, v202
	v_and_b32_e32 v241, 0xffff0000, v202
	v_lshlrev_b32_e32 v166, 16, v206
	v_and_b32_e32 v167, 0xffff0000, v206
	v_lshlrev_b32_e32 v242, 16, v203
	v_and_b32_e32 v243, 0xffff0000, v203
	v_lshlrev_b32_e32 v202, 16, v207
	v_and_b32_e32 v203, 0xffff0000, v207
	v_lshlrev_b32_e32 v206, 16, v208
	v_and_b32_e32 v207, 0xffff0000, v208
	v_lshlrev_b32_e32 v208, 16, v205
	v_pk_mul_f32 v[62:63], v[62:63], v[160:161]
	v_and_b32_e32 v161, 0xffff0000, v205
	v_rcp_f32_e32 v160, v208
	v_rcp_f32_e32 v161, v161
	v_pk_mul_f32 v[162:163], v[238:239], v[162:163]
	v_lshlrev_b32_e32 v244, 16, v204
	v_pk_mul_f32 v[58:59], v[58:59], v[162:163]
	v_lshlrev_b32_e32 v162, 16, v209
	v_and_b32_e32 v163, 0xffff0000, v209
	v_pk_mul_f32 v[160:161], v[160:161], v[162:163]
	v_and_b32_e32 v204, 0xffff0000, v204
	v_pk_mul_f32 v[46:47], v[46:47], v[160:161]
	v_rcp_f32_e32 v210, v210
	v_rcp_f32_e32 v211, v211
	v_rcp_f32_e32 v236, v236
	v_rcp_f32_e32 v237, v237
	v_rcp_f32_e32 v240, v240
	v_rcp_f32_e32 v241, v241
	v_rcp_f32_e32 v242, v242
	v_rcp_f32_e32 v243, v243
	v_rcp_f32_e32 v244, v244
	v_rcp_f32_e32 v245, v204
	v_pk_mul_f32 v[196:197], v[210:211], v[196:197]
	v_pk_mul_f32 v[164:165], v[236:237], v[164:165]
	v_pk_mul_f32 v[166:167], v[240:241], v[166:167]
	v_pk_mul_f32 v[202:203], v[242:243], v[202:203]
	v_pk_mul_f32 v[206:207], v[244:245], v[206:207]
	v_pk_mul_f32 v[60:61], v[60:61], v[196:197]
	v_pk_mul_f32 v[56:57], v[56:57], v[164:165]
	v_pk_mul_f32 v[52:53], v[52:53], v[166:167]
	v_pk_mul_f32 v[54:55], v[54:55], v[202:203]
	v_pk_mul_f32 v[44:45], v[44:45], v[206:207]
	s_waitcnt vmcnt(0) lgkmcnt(0)
;     __device__ __forceinline__ void mid(f32x4 (&acc)[2][2][4][2], const Unit& u, int wr, int wc, int fr, int fq) const {
;         const bf16* gb = G + (size_t)(u.pm * 256 + wr * 64 + fr) * 2048 + u.pn * 256 + wc * 32 + 8 * fq;
; #pragma unroll
;         for (int ai = 0; ai < 2; ++ai) { asm volatile("" : "+v"(gb));
;             u32x4 gp[4][2], gf[4][2];
; #pragma unroll
;             for (int m = 0; m < 4; ++m)
; #pragma unroll
;                 for (int bj = 0; bj < 2; ++bj) { const bf16* gr = gb + (size_t)(ai * 128 + m * 16) * 2048 + bj * 128; gp[m][bj] = *(const u32x4*)gr; gf[m][bj] = *(const u32x4*)(gr + 1024); }
; #pragma unroll
;             for (int m = 0; m < 4; ++m)
; #pragma unroll
;                 for (int bj = 0; bj < 2; ++bj) { const u32x4 p = gp[m][bj], f = gf[m][bj];
;                     acc[ai][bj][m][0][0] *= bflo(p.x) * __builtin_amdgcn_rcpf(bflo(f.x)); acc[ai][bj][m][0][1] *= bfhi(p.x) * __builtin_amdgcn_rcpf(bfhi(f.x));
;                     acc[ai][bj][m][0][2] *= bflo(p.y) * __builtin_amdgcn_rcpf(bflo(f.y)); acc[ai][bj][m][0][3] *= bfhi(p.y) * __builtin_amdgcn_rcpf(bfhi(f.y));
;                     acc[ai][bj][m][1][0] *= bflo(p.z) * __builtin_amdgcn_rcpf(bflo(f.z)); acc[ai][bj][m][1][1] *= bfhi(p.z) * __builtin_amdgcn_rcpf(bfhi(f.z));
;                     acc[ai][bj][m][1][2] *= bflo(p.w) * __builtin_amdgcn_rcpf(bflo(f.w)); acc[ai][bj][m][1][3] *= bfhi(p.w) * __builtin_amdgcn_rcpf(bfhi(f.w)); }
;             __builtin_amdgcn_sched_barrier(0); }
;     }
	v_lshlrev_b32_e32 v162, 16, v214
	v_and_b32_e32 v163, 0xffff0000, v214
	v_rcp_f32_e32 v162, v162
	v_rcp_f32_e32 v163, v163
	v_lshlrev_b32_e32 v160, 16, v222
	v_and_b32_e32 v161, 0xffff0000, v222
	v_pk_mul_f32 v[160:161], v[162:163], v[160:161]
	v_lshlrev_b32_e32 v162, 16, v215
	v_and_b32_e32 v163, 0xffff0000, v215
	v_rcp_f32_e32 v162, v162
	v_rcp_f32_e32 v163, v163
	v_pk_mul_f32 v[48:49], v[48:49], v[160:161]
	v_lshlrev_b32_e32 v160, 16, v223
	v_and_b32_e32 v161, 0xffff0000, v223
	v_pk_mul_f32 v[160:161], v[162:163], v[160:161]
	v_lshlrev_b32_e32 v162, 16, v216
	v_and_b32_e32 v163, 0xffff0000, v216
	v_rcp_f32_e32 v162, v162
	v_rcp_f32_e32 v163, v163
	v_pk_mul_f32 v[50:51], v[50:51], v[160:161]
	v_lshlrev_b32_e32 v160, 16, v224
	v_and_b32_e32 v161, 0xffff0000, v224
	v_pk_mul_f32 v[160:161], v[162:163], v[160:161]
	v_lshlrev_b32_e32 v162, 16, v217
	v_and_b32_e32 v163, 0xffff0000, v217
	v_rcp_f32_e32 v162, v162
	v_rcp_f32_e32 v163, v163
	v_pk_mul_f32 v[40:41], v[40:41], v[160:161]
	v_lshlrev_b32_e32 v160, 16, v225
	v_and_b32_e32 v161, 0xffff0000, v225
	v_pk_mul_f32 v[160:161], v[162:163], v[160:161]
	v_lshlrev_b32_e32 v162, 16, v230
	v_and_b32_e32 v163, 0xffff0000, v230
	v_rcp_f32_e32 v162, v162
	v_rcp_f32_e32 v163, v163
	v_pk_mul_f32 v[42:43], v[42:43], v[160:161]
	v_lshlrev_b32_e32 v160, 16, v226
	v_and_b32_e32 v161, 0xffff0000, v226
	v_pk_mul_f32 v[160:161], v[162:163], v[160:161]
	v_lshlrev_b32_e32 v162, 16, v231
	v_and_b32_e32 v163, 0xffff0000, v231
	v_rcp_f32_e32 v162, v162
	v_rcp_f32_e32 v163, v163
	v_pk_mul_f32 v[36:37], v[36:37], v[160:161]
	v_lshlrev_b32_e32 v160, 16, v227
	v_and_b32_e32 v161, 0xffff0000, v227
	v_pk_mul_f32 v[160:161], v[162:163], v[160:161]
	v_lshlrev_b32_e32 v162, 16, v232
	v_and_b32_e32 v163, 0xffff0000, v232
	v_rcp_f32_e32 v162, v162
	v_rcp_f32_e32 v163, v163
	v_pk_mul_f32 v[38:39], v[38:39], v[160:161]
	v_lshlrev_b32_e32 v160, 16, v228
	v_and_b32_e32 v161, 0xffff0000, v228
	v_pk_mul_f32 v[160:161], v[162:163], v[160:161]
	v_lshlrev_b32_e32 v162, 16, v233
	v_and_b32_e32 v163, 0xffff0000, v233
	v_rcp_f32_e32 v162, v162
	v_rcp_f32_e32 v163, v163
	v_pk_mul_f32 v[28:29], v[28:29], v[160:161]
	v_lshlrev_b32_e32 v160, 16, v229
	v_and_b32_e32 v161, 0xffff0000, v229
	v_pk_mul_f32 v[160:161], v[162:163], v[160:161]
	v_lshlrev_b32_e32 v162, 16, v156
	v_and_b32_e32 v156, 0xffff0000, v156
	v_pk_mul_f32 v[30:31], v[30:31], v[160:161]
	v_lshlrev_b32_e32 v160, 16, v152
	v_and_b32_e32 v161, 0xffff0000, v152
	v_lshlrev_b32_e32 v152, 16, v157
	v_rcp_f32_e32 v163, v156
	v_rcp_f32_e32 v156, v152
	v_and_b32_e32 v152, 0xffff0000, v157
	v_rcp_f32_e32 v157, v152
	v_lshlrev_b32_e32 v152, 16, v153
	v_and_b32_e32 v153, 0xffff0000, v153
	v_rcp_f32_e32 v162, v162
	v_pk_mul_f32 v[152:153], v[156:157], v[152:153]
	v_lshlrev_b32_e32 v156, 16, v158
	v_and_b32_e32 v157, 0xffff0000, v158
	v_rcp_f32_e32 v156, v156
	v_rcp_f32_e32 v157, v157
	v_pk_mul_f32 v[34:35], v[34:35], v[152:153]
	v_lshlrev_b32_e32 v152, 16, v154
	v_and_b32_e32 v153, 0xffff0000, v154
	v_lshlrev_b32_e32 v154, 16, v159
	v_pk_mul_f32 v[152:153], v[156:157], v[152:153]
	v_rcp_f32_e32 v156, v154
	v_and_b32_e32 v154, 0xffff0000, v159
	v_rcp_f32_e32 v157, v154
	v_pk_mul_f32 v[24:25], v[24:25], v[152:153]
	v_lshlrev_b32_e32 v152, 16, v155
	v_and_b32_e32 v153, 0xffff0000, v155
	v_pk_mul_f32 v[152:153], v[156:157], v[152:153]
	v_lshlrev_b32_e32 v154, 16, v148
	v_and_b32_e32 v148, 0xffff0000, v148
	v_pk_mul_f32 v[26:27], v[26:27], v[152:153]
	v_lshlrev_b32_e32 v152, 16, v144
	v_and_b32_e32 v153, 0xffff0000, v144
	v_lshlrev_b32_e32 v144, 16, v149
	v_rcp_f32_e32 v155, v148
	v_rcp_f32_e32 v148, v144
	v_and_b32_e32 v144, 0xffff0000, v149
	v_rcp_f32_e32 v149, v144
	v_lshlrev_b32_e32 v144, 16, v145
	v_and_b32_e32 v145, 0xffff0000, v145
	v_rcp_f32_e32 v154, v154
	v_pk_mul_f32 v[144:145], v[148:149], v[144:145]
	v_lshlrev_b32_e32 v148, 16, v150
	v_and_b32_e32 v149, 0xffff0000, v150
	v_rcp_f32_e32 v148, v148
	v_rcp_f32_e32 v149, v149
	v_pk_mul_f32 v[22:23], v[22:23], v[144:145]
	v_lshlrev_b32_e32 v144, 16, v146
	v_and_b32_e32 v145, 0xffff0000, v146
	v_lshlrev_b32_e32 v146, 16, v151
	v_pk_mul_f32 v[144:145], v[148:149], v[144:145]
	v_rcp_f32_e32 v148, v146
	v_and_b32_e32 v146, 0xffff0000, v151
	v_rcp_f32_e32 v149, v146
	v_pk_mul_f32 v[12:13], v[12:13], v[144:145]
	v_lshlrev_b32_e32 v144, 16, v147
	v_and_b32_e32 v145, 0xffff0000, v147
	v_pk_mul_f32 v[144:145], v[148:149], v[144:145]
	v_lshlrev_b32_e32 v146, 16, v140
	v_and_b32_e32 v140, 0xffff0000, v140
	v_pk_mul_f32 v[14:15], v[14:15], v[144:145]
	v_lshlrev_b32_e32 v144, 16, v136
	v_and_b32_e32 v145, 0xffff0000, v136
	v_lshlrev_b32_e32 v136, 16, v141
	v_rcp_f32_e32 v147, v140
	v_rcp_f32_e32 v140, v136
	v_and_b32_e32 v136, 0xffff0000, v141
	v_rcp_f32_e32 v141, v136
	v_lshlrev_b32_e32 v136, 16, v137
	v_and_b32_e32 v137, 0xffff0000, v137
	v_rcp_f32_e32 v146, v146
	v_pk_mul_f32 v[136:137], v[140:141], v[136:137]
	v_lshlrev_b32_e32 v140, 16, v142
	v_and_b32_e32 v141, 0xffff0000, v142
	v_rcp_f32_e32 v140, v140
	v_rcp_f32_e32 v141, v141
	v_pk_mul_f32 v[18:19], v[18:19], v[136:137]
	v_lshlrev_b32_e32 v136, 16, v138
	v_and_b32_e32 v137, 0xffff0000, v138
	v_lshlrev_b32_e32 v138, 16, v143
	v_pk_mul_f32 v[136:137], v[140:141], v[136:137]
	v_rcp_f32_e32 v140, v138
	v_and_b32_e32 v138, 0xffff0000, v143
	v_rcp_f32_e32 v141, v138
	v_pk_mul_f32 v[8:9], v[8:9], v[136:137]
	v_lshlrev_b32_e32 v136, 16, v139
	v_and_b32_e32 v137, 0xffff0000, v139
	v_pk_mul_f32 v[136:137], v[140:141], v[136:137]
	v_lshlrev_b32_e32 v138, 16, v132
	v_and_b32_e32 v132, 0xffff0000, v132
	v_pk_mul_f32 v[10:11], v[10:11], v[136:137]
	v_lshlrev_b32_e32 v136, 16, v128
	v_and_b32_e32 v137, 0xffff0000, v128
	v_lshlrev_b32_e32 v128, 16, v133
	v_rcp_f32_e32 v139, v132
	v_rcp_f32_e32 v132, v128
	v_and_b32_e32 v128, 0xffff0000, v133
	v_rcp_f32_e32 v133, v128
	v_lshlrev_b32_e32 v128, 16, v129
	v_and_b32_e32 v129, 0xffff0000, v129
	v_rcp_f32_e32 v138, v138
	v_pk_mul_f32 v[128:129], v[132:133], v[128:129]
	v_lshlrev_b32_e32 v132, 16, v134
	v_and_b32_e32 v133, 0xffff0000, v134
	v_rcp_f32_e32 v132, v132
	v_rcp_f32_e32 v133, v133
	v_pk_mul_f32 v[6:7], v[6:7], v[128:129]
	v_lshlrev_b32_e32 v128, 16, v130
	v_and_b32_e32 v129, 0xffff0000, v130
	v_lshlrev_b32_e32 v130, 16, v135
	v_pk_mul_f32 v[128:129], v[132:133], v[128:129]
	v_rcp_f32_e32 v132, v130
	v_and_b32_e32 v130, 0xffff0000, v135
	v_rcp_f32_e32 v133, v130
	v_pk_mul_f32 v[0:1], v[0:1], v[128:129]
	v_lshlrev_b32_e32 v128, 16, v131
	v_and_b32_e32 v129, 0xffff0000, v131
	v_pk_mul_f32 v[160:161], v[162:163], v[160:161]
	v_pk_mul_f32 v[152:153], v[154:155], v[152:153]
	v_pk_mul_f32 v[144:145], v[146:147], v[144:145]
	v_pk_mul_f32 v[136:137], v[138:139], v[136:137]
	v_pk_mul_f32 v[128:129], v[132:133], v[128:129]
	v_pk_mul_f32 v[32:33], v[32:33], v[160:161]
	v_pk_mul_f32 v[20:21], v[20:21], v[152:153]
	v_pk_mul_f32 v[16:17], v[16:17], v[144:145]
	v_pk_mul_f32 v[4:5], v[4:5], v[136:137]
	v_pk_mul_f32 v[2:3], v[2:3], v[128:129]
	s_branch .LBB0_512
